# prepA DeltaNet-conv task: six serialized pairs of 2-byte loads issued as one burst with a single wait (plus all earlier changes)
# speedup vs baseline: 1.0629x; 1.0629x over previous
; DI float bf2f(bf16_t b) { return __uint_as_float(((unsigned)b) << 16); }
; NI void prepA_row(const P& p, int l, int t0) {
;     ...
;       const bf16_t* src = U + (size_t)t0 * INP + (isq ? O_AQ : O_AK) + hd * 128 + ln;
;       const float* nwp = (isq ? p.in[I_AQN] : p.in[I_AKN]) + l * 128 + ln;
;       float x[RB][4], nw[4];
; #pragma unroll
;       for (int rr = 0; rr < RB; ++rr)
; #pragma unroll
;         for (int j = 0; j < 4; ++j) x[rr][j] = bf2f(src[(size_t)rr * INP + 32 * j]);
; #pragma unroll
;       for (int j = 0; j < 4; ++j) nw[j] = nwp[32 * j];
;       const float invf = exp2f(-(float)ln * (13.287712379549449f / 32.f));
;       bf16_t* dst = (bf16_t*)(ws + (isq ? WS_QA : WS_KA)) + ((size_t)hd * T + t0) * 128 + ln;
; #pragma unroll
;       for (int rr = 0; rr < RB; ++rr) {
;         float ss = x[rr][0] * x[rr][0] + x[rr][1] * x[rr][1] + x[rr][2] * x[rr][2] + x[rr][3] * x[rr][3];
;         ss = hw_sum(ss);
;         const float rstd = rsqrtf(ss * (1.f / 128.f) + EPS);
.LBB0_355:
	s_andn2_saveexec_b64 s[22:23], s[42:43]
	s_cbranch_execz .LBB0_300
	v_cmp_gt_i32_e32 vcc, 4, v1
	v_add_u32_e32 v29, -4, v1
	v_readlane_b32 s76, v252, 28
	v_cndmask_b32_e32 v29, v29, v1, vcc
	v_cndmask_b32_e64 v96, v236, 0, vcc
	v_lshlrev_b32_e32 v40, 7, v29
	v_lshl_add_u64 v[38:39], s[30:31], 0, v[96:97]
	v_ashrrev_i32_e32 v41, 31, v40
	v_readlane_b32 s79, v252, 31
	v_readlane_b32 s81, v252, 33
	v_lshl_add_u64 v[38:39], v[40:41], 1, v[38:39]
	v_lshlrev_b32_e32 v96, 1, v0
	v_readlane_b32 s78, v252, 30
	v_readlane_b32 s80, v252, 32
	v_mov_b32_e32 v31, s81
	v_mov_b32_e32 v33, s79
	s_waitcnt vmcnt(14)
	v_lshl_add_u64 v[56:57], v[38:39], 0, v[96:97]
	v_cndmask_b32_e32 v39, v31, v33, vcc
	v_mov_b32_e32 v31, s80
	v_mov_b32_e32 v33, s78
	v_readlane_b32 s0, v255, 19
	v_cndmask_b32_e32 v38, v31, v33, vcc
	v_readlane_b32 s1, v255, 20
	v_lshlrev_b32_e32 v44, 2, v0
	v_mov_b32_e32 v45, v97
	v_lshl_add_u64 v[38:39], s[0:1], 2, v[38:39]
	v_add_co_u32_e64 v40, s[0:1], s33, v56
	v_lshl_add_u64 v[38:39], v[38:39], 0, v[44:45]
	s_nop 0
	v_addc_co_u32_e64 v41, s[0:1], 0, v57, s[0:1]
	global_load_ushort v98, v[40:41], off offset:3584
	global_load_ushort v99, v[40:41], off offset:3712
	s_movk_i32 s0, 0x5000
	v_mov_b64_e32 v[58:59], s[28:29]
	v_readlane_b32 s77, v252, 29
	s_mov_b32 s77, 0x800000
	v_readlane_b32 s82, v252, 34
	v_readlane_b32 s83, v252, 35
	v_readlane_b32 s82, v254, 62
	v_readlane_b32 s78, v254, 60
	v_readlane_b32 s83, v254, 63
	v_readlane_b32 s79, v254, 61
	v_readlane_b32 s84, v252, 36
	v_readlane_b32 s85, v252, 37
	v_readlane_b32 s86, v252, 38
	v_readlane_b32 s87, v252, 39
	v_readlane_b32 s88, v252, 40
	v_readlane_b32 s89, v252, 41
	v_readlane_b32 s90, v252, 42
	v_readlane_b32 s91, v252, 43
	global_load_ushort v100, v[40:41], off offset:3648
	global_load_ushort v101, v[40:41], off offset:3776
	v_add_co_u32_e64 v40, s[0:1], s0, v56
	v_addc_co_u32_e64 v41, s[0:1], 0, v57, s[0:1]
	global_load_ushort v102, v[40:41], off offset:3072
	global_load_ushort v103, v[40:41], off offset:3200
	s_mov_b32 s0, 0x8000
	v_add_co_u32_e64 v42, s[0:1], s0, v56
	global_load_ushort v104, v[40:41], off offset:3136
	global_load_ushort v105, v[40:41], off offset:3264
	v_addc_co_u32_e64 v43, s[0:1], 0, v57, s[0:1]
	s_movk_i32 s0, 0x2100
	s_nop 0
	v_mad_i64_i32 v[58:59], s[0:1], v29, s0, v[58:59]
	v_lshlrev_b64 v[58:59], 8, v[58:59]
	v_xor_b32_e32 v29, 16, v210
	global_load_ushort v106, v[42:43], off offset:2560
	global_load_ushort v107, v[42:43], off offset:2688
	global_load_ushort v108, v[42:43], off offset:2624
	global_load_ushort v109, v[42:43], off offset:2752
	global_load_dword v110, v[38:39], off
	global_load_dword v111, v[38:39], off offset:128
	global_load_dword v112, v[38:39], off offset:256
	global_load_dword v113, v[38:39], off offset:384
	v_cndmask_b32_e32 v38, v228, v242, vcc
	v_mov_b32_e32 v39, v97
	v_lshl_add_u64 v[38:39], s[94:95], 0, v[38:39]
	v_lshl_add_u64 v[38:39], v[38:39], 0, v[58:59]
	v_lshl_add_u64 v[38:39], v[38:39], 0, v[96:97]
	v_and_b32_e32 v31, 64, v210
	v_add_u32_e32 v58, 64, v31
	v_cmp_lt_i32_e32 vcc, v29, v58
	v_cndmask_b32_e32 v29, v210, v29, vcc
	v_lshlrev_b32_e32 v37, 2, v29
	v_xor_b32_e32 v29, 8, v210
	v_cmp_lt_i32_e32 vcc, v29, v58
	s_nop 1
	v_cndmask_b32_e32 v29, v210, v29, vcc
	v_lshlrev_b32_e32 v35, 2, v29
	v_xor_b32_e32 v29, 4, v210
	v_cmp_lt_i32_e32 vcc, v29, v58
	s_nop 1
	v_cndmask_b32_e32 v29, v210, v29, vcc
	v_lshlrev_b32_e32 v33, 2, v29
	v_xor_b32_e32 v29, 2, v210
	v_cmp_lt_i32_e32 vcc, v29, v58
	s_nop 1
	v_cndmask_b32_e32 v29, v210, v29, vcc
	v_lshlrev_b32_e32 v31, 2, v29
	v_xor_b32_e32 v29, 1, v210
	v_cmp_lt_i32_e32 vcc, v29, v58
	global_load_ushort v114, v[56:57], off
	global_load_ushort v115, v[56:57], off offset:128
	global_load_ushort v116, v[56:57], off offset:64
	s_nop 0
	global_load_ushort v117, v[56:57], off offset:192
	v_cndmask_b32_e32 v29, v210, v29, vcc
	v_lshlrev_b32_e32 v29, 2, v29
	s_waitcnt vmcnt(0)
	v_lshlrev_b32_e32 v52, 16, v98
	v_lshlrev_b32_e32 v53, 16, v99
	s_nop 2
	v_lshlrev_b32_e32 v54, 16, v100
	s_nop 0
	v_lshlrev_b32_e32 v55, 16, v101
	s_nop 3
	v_lshlrev_b32_e32 v48, 16, v102
	v_lshlrev_b32_e32 v49, 16, v103
	s_nop 4
	v_lshlrev_b32_e32 v50, 16, v104
	v_lshlrev_b32_e32 v51, 16, v105
	s_nop 1
	v_lshlrev_b32_e32 v40, 16, v106
	v_lshlrev_b32_e32 v41, 16, v107
	s_nop 4
	v_lshlrev_b32_e32 v42, 16, v108
	s_nop 2
	v_lshlrev_b32_e32 v43, 16, v109
	s_nop 4
	v_lshlrev_b32_e32 v58, 16, v114
	v_lshlrev_b32_e32 v59, 16, v115
	v_mov_b32_e32 v46, v110
	v_mov_b32_e32 v44, v111
	v_mov_b32_e32 v47, v112
	v_mov_b32_e32 v45, v113
	v_mov_b32_e32 v60, v116
	v_mov_b32_e32 v56, v117
	v_lshlrev_b32_e32 v57, 16, v56
	v_lshlrev_b32_e32 v56, 16, v60
	v_mov_b32_e32 v60, v58
	v_mov_b32_e32 v61, v56
	v_pk_mul_f32 v[60:61], v[60:61], v[60:61]
	v_mov_b32_e32 v62, v59
	v_mov_b32_e32 v63, v57
	v_pk_mul_f32 v[62:63], v[62:63], v[62:63]
	v_add_f32_e32 v60, v60, v61
	v_add_f32_e32 v60, v60, v62
	v_add_f32_e32 v60, v60, v63
	ds_bpermute_b32 v61, v37, v60
	s_waitcnt lgkmcnt(0)
	v_add_f32_e32 v60, v60, v61
	ds_bpermute_b32 v61, v35, v60
	s_waitcnt lgkmcnt(0)
	v_add_f32_e32 v60, v60, v61
	ds_bpermute_b32 v61, v33, v60
	s_waitcnt lgkmcnt(0)
	v_add_f32_e32 v60, v60, v61
	ds_bpermute_b32 v61, v31, v60
	s_waitcnt lgkmcnt(0)
	v_add_f32_e32 v60, v60, v61
	ds_bpermute_b32 v61, v29, v60
	s_waitcnt lgkmcnt(0)
; DI bf16_t f2bf(float x) { unsigned u = __float_as_uint(x); u += 0x7fffu + ((u >> 16) & 1u); return (bf16_t)(u >> 16); }
; NI void prepA_row(const P& p, int l, int t0) {
;     ...
;       for (int rr = 0; rr < RB; ++rr) {
;         float ss = x[rr][0] * x[rr][0] + x[rr][1] * x[rr][1] + x[rr][2] * x[rr][2] + x[rr][3] * x[rr][3];
;         ss = hw_sum(ss);
;         const float rstd = rsqrtf(ss * (1.f / 128.f) + EPS);
; #pragma unroll
;         for (int j = 0; j < 4; ++j) x[rr][j] = x[rr][j] * rstd * nw[j];
;         if (lat) {
;           const int tt = t0 + rr - NCTX, rpos = tt >> 6, cpos = tt & 63;
;           float sn, c;
;           sincos_rev((float)rpos * invf, sn, c);
;           float a = x[rr][0] * c - x[rr][1] * sn, b = x[rr][0] * sn + x[rr][1] * c; x[rr][0] = a; x[rr][1] = b;
;           sincos_rev((float)cpos * invf, sn, c);
;           a = x[rr][2] * c - x[rr][3] * sn; b = x[rr][2] * sn + x[rr][3] * c; x[rr][2] = a; x[rr][3] = b;
;         }
; #pragma unroll
;         for (int j = 0; j < 4; ++j) dst[rr * 128 + 32 * j] = f2bf(x[rr][j]);
;       }
	v_add_f32_e32 v60, v60, v61
	v_fmamk_f32 v60, v60, 0x3c000000, v206
	v_cmp_gt_f32_e32 vcc, s77, v60
	v_mul_f32_e32 v61, 0x4b800000, v60
	s_nop 0
	v_cndmask_b32_e32 v60, v60, v61, vcc
	v_rsq_f32_e32 v60, v60
	s_nop 0
	v_mul_f32_e32 v61, 0x45800000, v60
	v_cndmask_b32_e32 v60, v60, v61, vcc
	v_pk_mul_f32 v[56:57], v[60:61], v[56:57] op_sel_hi:[0,1]
	v_pk_mul_f32 v[58:59], v[60:61], v[58:59] op_sel_hi:[0,1]
	v_pk_mul_f32 v[56:57], v[44:45], v[56:57]
	v_pk_mul_f32 v[58:59], v[46:47], v[58:59]
	v_pk_mul_f32 v[62:63], v[12:13], v[56:57]
	v_pk_mul_f32 v[60:61], v[14:15], v[56:57]
	v_pk_fma_f32 v[62:63], v[14:15], v[58:59], v[62:63] neg_lo:[0,0,1] neg_hi:[0,0,1]
	v_pk_fma_f32 v[60:61], v[12:13], v[58:59], v[60:61]
	v_cndmask_b32_e64 v58, v58, v62, s[20:21]
	v_cndmask_b32_e64 v56, v56, v60, s[20:21]
	v_bfe_u32 v60, v58, 16, 1
	v_add3_u32 v58, v58, v60, s61
	global_store_short_d16_hi v[38:39], v58, off
	v_bfe_u32 v58, v56, 16, 1
	v_cndmask_b32_e64 v59, v59, v63, s[20:21]
	v_add3_u32 v56, v56, v58, s61
	global_store_short_d16_hi v[38:39], v56, off offset:64
	v_bfe_u32 v56, v59, 16, 1
	v_cndmask_b32_e64 v57, v57, v61, s[20:21]
	v_add3_u32 v56, v59, v56, s61
	global_store_short_d16_hi v[38:39], v56, off offset:128
	v_bfe_u32 v56, v57, 16, 1
	v_add3_u32 v56, v57, v56, s61
	global_store_short_d16_hi v[38:39], v56, off offset:192
	v_mov_b32_e32 v56, v52
	v_mov_b32_e32 v57, v54
	v_pk_mul_f32 v[56:57], v[56:57], v[56:57]
	v_mov_b32_e32 v58, v53
	v_mov_b32_e32 v59, v55
	v_pk_mul_f32 v[58:59], v[58:59], v[58:59]
	v_add_f32_e32 v56, v56, v57
	v_add_f32_e32 v56, v56, v58
	v_add_f32_e32 v56, v56, v59
	ds_bpermute_b32 v57, v37, v56
	s_waitcnt lgkmcnt(0)
	v_add_f32_e32 v56, v56, v57
	ds_bpermute_b32 v57, v35, v56
	s_waitcnt lgkmcnt(0)
	v_add_f32_e32 v56, v56, v57
	ds_bpermute_b32 v57, v33, v56
	s_waitcnt lgkmcnt(0)
	v_add_f32_e32 v56, v56, v57
	ds_bpermute_b32 v57, v31, v56
	s_waitcnt lgkmcnt(0)
	v_add_f32_e32 v56, v56, v57
	ds_bpermute_b32 v57, v29, v56
	s_waitcnt lgkmcnt(0)
	v_add_f32_e32 v56, v56, v57
	v_fmamk_f32 v56, v56, 0x3c000000, v206
	v_cmp_gt_f32_e32 vcc, s77, v56
	v_mul_f32_e32 v57, 0x4b800000, v56
	s_nop 0
	v_cndmask_b32_e32 v56, v56, v57, vcc
	v_rsq_f32_e32 v56, v56
	s_nop 0
	v_mul_f32_e32 v57, 0x45800000, v56
	v_cndmask_b32_e32 v56, v56, v57, vcc
	v_pk_mul_f32 v[54:55], v[56:57], v[54:55] op_sel_hi:[0,1]
	v_pk_mul_f32 v[52:53], v[56:57], v[52:53] op_sel_hi:[0,1]
	v_pk_mul_f32 v[54:55], v[44:45], v[54:55]
	v_pk_mul_f32 v[52:53], v[46:47], v[52:53]
	v_pk_mul_f32 v[58:59], v[16:17], v[54:55]
	v_pk_mul_f32 v[56:57], v[18:19], v[54:55]
	v_pk_fma_f32 v[58:59], v[18:19], v[52:53], v[58:59] neg_lo:[0,0,1] neg_hi:[0,0,1]
	v_pk_fma_f32 v[56:57], v[16:17], v[52:53], v[56:57]
	v_cndmask_b32_e64 v52, v52, v58, s[20:21]
	v_cndmask_b32_e64 v54, v54, v56, s[20:21]
	v_bfe_u32 v56, v52, 16, 1
	v_add3_u32 v52, v52, v56, s61
	global_store_short_d16_hi v[38:39], v52, off offset:256
	v_bfe_u32 v52, v54, 16, 1
	v_cndmask_b32_e64 v53, v53, v59, s[20:21]
	v_add3_u32 v52, v54, v52, s61
	global_store_short_d16_hi v[38:39], v52, off offset:320
	v_bfe_u32 v52, v53, 16, 1
	v_cndmask_b32_e64 v55, v55, v57, s[20:21]
	v_add3_u32 v52, v53, v52, s61
	global_store_short_d16_hi v[38:39], v52, off offset:384
	v_bfe_u32 v52, v55, 16, 1
	v_add3_u32 v52, v55, v52, s61
	global_store_short_d16_hi v[38:39], v52, off offset:448
	v_mov_b32_e32 v52, v48
	v_mov_b32_e32 v53, v50
	v_pk_mul_f32 v[52:53], v[52:53], v[52:53]
	v_mov_b32_e32 v54, v49
	v_mov_b32_e32 v55, v51
	v_pk_mul_f32 v[54:55], v[54:55], v[54:55]
	v_add_f32_e32 v52, v52, v53
	v_add_f32_e32 v52, v52, v54
	v_add_f32_e32 v52, v52, v55
	ds_bpermute_b32 v53, v37, v52
	s_waitcnt lgkmcnt(0)
; DI bf16_t f2bf(float x) { unsigned u = __float_as_uint(x); u += 0x7fffu + ((u >> 16) & 1u); return (bf16_t)(u >> 16); }
; NI void prepA_row(const P& p, int l, int t0) {
;     ...
;       for (int rr = 0; rr < RB; ++rr) {
;         float ss = x[rr][0] * x[rr][0] + x[rr][1] * x[rr][1] + x[rr][2] * x[rr][2] + x[rr][3] * x[rr][3];
;         ss = hw_sum(ss);
;         const float rstd = rsqrtf(ss * (1.f / 128.f) + EPS);
; #pragma unroll
;         for (int j = 0; j < 4; ++j) x[rr][j] = x[rr][j] * rstd * nw[j];
;         if (lat) {
;           const int tt = t0 + rr - NCTX, rpos = tt >> 6, cpos = tt & 63;
;           float sn, c;
;           sincos_rev((float)rpos * invf, sn, c);
;           float a = x[rr][0] * c - x[rr][1] * sn, b = x[rr][0] * sn + x[rr][1] * c; x[rr][0] = a; x[rr][1] = b;
;           sincos_rev((float)cpos * invf, sn, c);
;           a = x[rr][2] * c - x[rr][3] * sn; b = x[rr][2] * sn + x[rr][3] * c; x[rr][2] = a; x[rr][3] = b;
;         }
; #pragma unroll
;         for (int j = 0; j < 4; ++j) dst[rr * 128 + 32 * j] = f2bf(x[rr][j]);
;       }
	v_add_f32_e32 v52, v52, v53
	ds_bpermute_b32 v53, v35, v52
	s_waitcnt lgkmcnt(0)
	v_add_f32_e32 v52, v52, v53
	ds_bpermute_b32 v53, v33, v52
	s_waitcnt lgkmcnt(0)
	v_add_f32_e32 v52, v52, v53
	ds_bpermute_b32 v53, v31, v52
	s_waitcnt lgkmcnt(0)
	v_add_f32_e32 v52, v52, v53
	ds_bpermute_b32 v53, v29, v52
	s_waitcnt lgkmcnt(0)
	v_add_f32_e32 v52, v52, v53
	v_fmamk_f32 v52, v52, 0x3c000000, v206
	v_cmp_gt_f32_e32 vcc, s77, v52
	v_mul_f32_e32 v53, 0x4b800000, v52
	s_nop 0
	v_cndmask_b32_e32 v52, v52, v53, vcc
	v_rsq_f32_e32 v52, v52
	s_nop 0
	v_mul_f32_e32 v53, 0x45800000, v52
	v_cndmask_b32_e32 v52, v52, v53, vcc
	v_pk_mul_f32 v[50:51], v[52:53], v[50:51] op_sel_hi:[0,1]
	v_pk_mul_f32 v[48:49], v[52:53], v[48:49] op_sel_hi:[0,1]
	v_pk_mul_f32 v[50:51], v[44:45], v[50:51]
	v_pk_mul_f32 v[48:49], v[46:47], v[48:49]
	v_pk_mul_f32 v[54:55], v[20:21], v[50:51]
	v_pk_mul_f32 v[52:53], v[22:23], v[50:51]
	v_pk_fma_f32 v[54:55], v[22:23], v[48:49], v[54:55] neg_lo:[0,0,1] neg_hi:[0,0,1]
	v_pk_fma_f32 v[52:53], v[20:21], v[48:49], v[52:53]
	v_cndmask_b32_e64 v48, v48, v54, s[20:21]
	v_cndmask_b32_e64 v50, v50, v52, s[20:21]
	v_bfe_u32 v52, v48, 16, 1
	v_add3_u32 v48, v48, v52, s61
	global_store_short_d16_hi v[38:39], v48, off offset:512
	v_bfe_u32 v48, v50, 16, 1
	v_cndmask_b32_e64 v49, v49, v55, s[20:21]
	v_add3_u32 v48, v50, v48, s61
	global_store_short_d16_hi v[38:39], v48, off offset:576
	v_bfe_u32 v48, v49, 16, 1
	v_cndmask_b32_e64 v51, v51, v53, s[20:21]
	v_add3_u32 v48, v49, v48, s61
	global_store_short_d16_hi v[38:39], v48, off offset:640
	v_bfe_u32 v48, v51, 16, 1
	v_add3_u32 v48, v51, v48, s61
	global_store_short_d16_hi v[38:39], v48, off offset:704
	v_mov_b32_e32 v48, v40
	v_mov_b32_e32 v49, v42
	v_pk_mul_f32 v[48:49], v[48:49], v[48:49]
	v_mov_b32_e32 v50, v41
	v_mov_b32_e32 v51, v43
	v_pk_mul_f32 v[50:51], v[50:51], v[50:51]
	v_add_f32_e32 v48, v48, v49
	v_add_f32_e32 v48, v48, v50
	v_add_f32_e32 v48, v48, v51
	ds_bpermute_b32 v37, v37, v48
	s_waitcnt lgkmcnt(0)
	v_add_f32_e32 v37, v48, v37
	ds_bpermute_b32 v35, v35, v37
	s_waitcnt lgkmcnt(0)
	v_add_f32_e32 v35, v37, v35
	ds_bpermute_b32 v33, v33, v35
	s_waitcnt lgkmcnt(0)
	v_add_f32_e32 v33, v35, v33
	ds_bpermute_b32 v31, v31, v33
	s_waitcnt lgkmcnt(0)
	v_add_f32_e32 v31, v33, v31
	ds_bpermute_b32 v29, v29, v31
	s_waitcnt lgkmcnt(0)
	v_add_f32_e32 v29, v31, v29
	v_fmamk_f32 v29, v29, 0x3c000000, v206
	v_cmp_gt_f32_e32 vcc, s77, v29
	v_mul_f32_e32 v31, 0x4b800000, v29
	s_nop 0
	v_cndmask_b32_e32 v29, v29, v31, vcc
	v_rsq_f32_e32 v29, v29
	s_nop 0
	v_mul_f32_e32 v31, 0x45800000, v29
	v_cndmask_b32_e32 v48, v29, v31, vcc
	v_pk_mul_f32 v[42:43], v[48:49], v[42:43] op_sel_hi:[0,1]
	v_pk_mul_f32 v[40:41], v[48:49], v[40:41] op_sel_hi:[0,1]
	v_pk_mul_f32 v[42:43], v[44:45], v[42:43]
	v_pk_mul_f32 v[40:41], v[46:47], v[40:41]
	v_pk_mul_f32 v[46:47], v[24:25], v[42:43]
	v_pk_mul_f32 v[44:45], v[26:27], v[42:43]
	v_pk_fma_f32 v[46:47], v[26:27], v[40:41], v[46:47] neg_lo:[0,0,1] neg_hi:[0,0,1]
	v_pk_fma_f32 v[44:45], v[24:25], v[40:41], v[44:45]
	v_cndmask_b32_e64 v35, v40, v46, s[20:21]
	v_bfe_u32 v37, v35, 16, 1
	v_cndmask_b32_e64 v31, v42, v44, s[20:21]
	v_add3_u32 v35, v35, v37, s61
	global_store_short_d16_hi v[38:39], v35, off offset:768
	v_bfe_u32 v35, v31, 16, 1
	v_cndmask_b32_e64 v33, v41, v47, s[20:21]
	v_add3_u32 v31, v31, v35, s61
	global_store_short_d16_hi v[38:39], v31, off offset:832
	v_bfe_u32 v31, v33, 16, 1
	v_cndmask_b32_e64 v29, v43, v45, s[20:21]
	v_add3_u32 v31, v33, v31, s61
	global_store_short_d16_hi v[38:39], v31, off offset:896
	v_bfe_u32 v31, v29, 16, 1
	v_add3_u32 v29, v29, v31, s61
	global_store_short_d16_hi v[38:39], v29, off offset:960
	s_branch .LBB0_300
